# attention meta tile: the 12 PV MFMAs whose P operand is the exact-zero padding probability (and their 12 LDS reads) removed; real key group starts from the zero accumulator
# speedup vs baseline: 1.0077x; 1.0077x over previous
; DI void attn_item(const Params& p, unsigned char* lds, int b, int hd, int qb, float lam) {
;     ...
;     const int qs = qb * 128 + rt * 32 + l31;
;     const size_t grow = (size_t)b * 4096 + qs;
;     bf16x8 qf[4];
; #pragma unroll
;     for (int ks = 0; ks < 4; ++ks) qf[ks] = *(const bf16x8*)(aq + grow * 1024 + hd * 128 + sub * 64 + ks * 16 + 8 * h);
;     f32x16 O[4];
; #pragma unroll
;     for (int d = 0; d < 4; ++d)
; #pragma unroll
;         for (int i = 0; i < 16; ++i) O[d][i] = 0.f;
;     float m = 0.f, l = 0.f;
;     const int T = 2 * qb + 3;
;     u32x4 k0r[2], v0r[2];
;     const int krow_ = tid >> 4, kc_ = tid & 15, vdv_ = tid >> 3, vc_ = tid & 7;
;     const bf16_t* kp = ak + ((size_t)b * 4096 + krow_) * 1024 + hd * 128 + kc_ * 8;
;     const bf16_t* vp_ = avT + ((size_t)(b * 8 + hd) * 128 + vdv_) * 4096 + vc_ * 8;
;     ...
;     {
;         const bf16_t* km_ = akm + (size_t)krow_ * 1024 + hd * 128 + kc_ * 8;
;         k0r[0] = *(const u32x4*)km_; k0r[1] = *(const u32x4*)(km_ + 32 * 1024);
;         const bf16_t* vm_ = avTm + (size_t)(hd * 128 + vdv_) * 64 + vc_ * 8;
;         v0r[0] = *(const u32x4*)vm_; v0r[1] = *(const u32x4*)(vm_ + 64 * 64);
;     }
;     u32x4 k1r[2], v1r[2];
;     A_LOAD_REAL(k1r, v1r);
; #pragma unroll
;     for (int ks = 0; ks < 4; ++ks) asm volatile("" : "+v"(qf[ks]));
;     A_STORE(k0r, v0r, 0);
;     __syncthreads();
; DI void phase2(const Params& p, unsigned char* lds) {
;     ...
;         const unsigned item = (unsigned)__builtin_amdgcn_readfirstlane((int)sItem[0]);
;         __syncthreads();
;         if (item == 0xffffffffu) break;
;         const unsigned x = item >> 16, idx = item & 0xffffu;
;         if (idx < N_GLA) { const unsigned gi = x * N_GLA + idx; gla_item<GLA_DL>(p, lds, gi / (4 * NSL), (gi / NSL) & 3, gi % NSL); }
;         else { const unsigned a = idx - N_GLA, pair = 4 * x + ((a >> 2) & 3); attn_item(p, lds, pair & 3, pair >> 2, 31 - (int)(((a >> 4) << 2) + (a & 3)), lam); }
.LBB0_1809:
	s_or_b64 exec, exec, s[4:5]
	s_add_i32 s0, 0, 0x25000
	s_cmp_lg_u32 s0, -1
	s_cselect_b32 s0, s0, 0
	s_cselect_b32 s4, s57, 0
	s_waitcnt vmcnt(0)
	v_mov_b32_e32 v2, s0
	v_mov_b32_e32 v3, s4
	s_waitcnt lgkmcnt(0)
	s_barrier
	ds_read_b32 v1, v2
	s_waitcnt vmcnt(0) lgkmcnt(0)
	s_barrier
	v_readfirstlane_b32 s8, v1
	s_cmp_eq_u32 s8, -1
	s_cbranch_scc1 .LBB0_1823
	s_lshr_b32 s9, s8, 16
	s_and_b32 s0, s8, 0xffff
	s_cmp_gt_u32 s0, 7
	s_mov_b64 s[4:5], -1
	s_cbranch_scc0 .LBB0_1831
	s_add_i32 s4, s0, -8
	s_lshr_b32 s0, s4, 2
	s_and_b32 s0, s0, 0x3ffffffc
	s_and_b32 s5, s8, 3
	s_or_b32 s0, s0, s5
	v_mov_b32_e32 v132, v186
	s_sub_i32 s0, 31, s0
	s_lshl_b32 s6, s0, 7
	v_lshrrev_b32_e32 v1, 1, v132
	v_and_b32_e32 v146, 31, v132
	v_and_b32_e32 v148, 0x60, v1
	s_bfe_u32 s11, s4, 0x20002
	v_or3_b32 v138, v148, s6, v146
	s_lshl_b32 s54, s11, 12
	v_ashrrev_i32_e32 v139, 31, v138
	v_lshl_add_u64 v[2:3], v[138:139], 0, s[54:55]
	v_ashrrev_i32_e32 v147, 8, v132
	v_lshlrev_b64 v[136:137], 11, v[2:3]
	v_lshl_add_u64 v[2:3], s[68:69], 0, v[136:137]
	s_lshl_b32 s6, s9, 8
	s_mov_b32 s7, s55
	v_lshlrev_b32_e32 v4, 6, v147
	v_lshl_add_u64 v[2:3], v[2:3], 0, s[6:7]
	v_ashrrev_i32_e32 v5, 31, v4
	v_lshl_add_u64 v[2:3], v[4:5], 1, v[2:3]
	v_ashrrev_i32_e32 v4, 4, v132
	v_ashrrev_i32_e32 v5, 31, v4
	v_lshlrev_b64 v[12:13], 11, v[4:5]
	v_bfe_u32 v149, v132, 5, 1
	v_lshlrev_b32_e32 v1, 4, v132
	v_lshl_add_u64 v[12:13], s[64:65], 0, v[12:13]
	v_lshlrev_b32_e32 v98, 4, v149
	v_and_b32_e32 v140, 0xf0, v1
	v_mov_b32_e32 v141, v99
	v_lshl_add_u64 v[12:13], v[12:13], 0, s[6:7]
	v_lshl_add_u64 v[2:3], v[2:3], 0, v[98:99]
	v_lshl_add_u64 v[12:13], v[12:13], 0, v[140:141]
	global_load_dwordx4 v[100:103], v[2:3], off
	global_load_dwordx4 v[104:107], v[2:3], off offset:32
	global_load_dwordx4 v[108:111], v[2:3], off offset:64
	global_load_dwordx4 v[112:115], v[2:3], off offset:96
	global_load_dwordx4 v[116:119], v[12:13], off
	v_add_co_u32_e32 v2, vcc, s43, v12
	s_lshl_b32 s10, s9, 7
	v_ashrrev_i32_e32 v6, 3, v132
	v_addc_co_u32_e32 v3, vcc, 0, v13, vcc
	global_load_dwordx4 v[120:123], v[2:3], off
	v_add_u32_e32 v2, s10, v6
	v_ashrrev_i32_e32 v3, 31, v2
	v_lshlrev_b64 v[2:3], 7, v[2:3]
	v_and_b32_e32 v10, 0x70, v1
	v_mov_b32_e32 v11, v99
	v_lshl_add_u64 v[2:3], s[62:63], 0, v[2:3]
	v_lshl_add_u64 v[2:3], v[2:3], 0, v[10:11]
	global_load_dwordx4 v[124:127], v[2:3], off
	v_lshl_add_u64 v[8:9], v[4:5], 0, s[54:55]
	v_lshlrev_b64 v[8:9], 11, v[8:9]
	v_add_co_u32_e32 v2, vcc, s56, v2
	v_lshl_add_u64 v[8:9], s[44:45], 0, v[8:9]
	s_lshl_b32 s11, s11, 10
	v_addc_co_u32_e32 v3, vcc, 0, v3, vcc
	v_lshl_add_u64 v[8:9], v[8:9], 0, s[6:7]
	s_add_i32 s54, s11, s10
	v_ashrrev_i32_e32 v7, 31, v6
	global_load_dwordx4 v[128:131], v[2:3], off
	v_lshl_add_u64 v[82:83], v[8:9], 0, v[140:141]
	v_lshl_add_u64 v[8:9], v[6:7], 0, s[54:55]
	v_lshlrev_b64 v[8:9], 13, v[8:9]
	v_lshl_add_u64 v[8:9], s[60:61], 0, v[8:9]
	v_add_co_u32_e32 v2, vcc, s43, v82
	v_lshl_add_u64 v[84:85], v[8:9], 0, v[10:11]
	s_nop 0
	v_addc_co_u32_e32 v3, vcc, 0, v83, vcc
	v_add_co_u32_e32 v8, vcc, s74, v84
	global_load_dwordx4 v[74:77], v[82:83], off
	global_load_dwordx4 v[70:73], v[84:85], off
	v_addc_co_u32_e32 v9, vcc, 0, v85, vcc
	global_load_dwordx4 v[78:81], v[2:3], off
	global_load_dwordx4 v[66:69], v[8:9], off
	v_lshlrev_b32_e32 v2, 3, v132
	v_mul_lo_u32 v139, v4, s75
	v_add_u32_e32 v4, 0x200, v132
	v_and_b32_e32 v150, 0x60, v1
	v_and_b32_e32 v151, 8, v2
	v_lshrrev_b32_e32 v5, 4, v4
	v_add3_u32 v1, 0, v150, v151
	v_mul_lo_u32 v152, v6, s52
	v_add_u32_e32 v3, 0, v140
	v_mul_lo_u32 v141, v5, s75
	v_add_u32_e32 v97, v1, v152
	v_add_u32_e32 v87, v3, v139
	v_add_u32_e32 v96, v3, v141
	v_add_u32_e32 v2, 0x4000, v97
	s_waitcnt vmcnt(11)
	s_waitcnt vmcnt(10)
	s_waitcnt vmcnt(9)
	s_waitcnt vmcnt(8)
	s_waitcnt vmcnt(7)
	ds_write_b128 v87, v[116:119]
	v_mad_u32_u24 v42, v146, s75, 0
	v_lshl_or_b32 v154, v147, 7, v98
	s_waitcnt vmcnt(6)
	ds_write_b128 v96, v[120:123]
	s_waitcnt vmcnt(5)
	ds_write2_b64 v2, v[124:125], v[126:127] offset0:128 offset1:130
	v_lshrrev_b32_e32 v2, 3, v4
	v_mul_lo_u32 v153, v2, s52
	v_add_u32_e32 v155, v1, v153
	v_add_u32_e32 v1, 0x4000, v155
	s_waitcnt vmcnt(4)
	ds_write2_b64 v1, v[128:129], v[130:131] offset0:128 offset1:130
	v_add_u32_e32 v1, v42, v154
	s_waitcnt lgkmcnt(0)
	s_barrier
; #define MFMA32(a, b, c) __builtin_amdgcn_mfma_f32_32x32x16_bf16((a), (b), (c), 0, 0, 0)
; DI void attn_pv(const unsigned char* sV, int l31, int h, const bf16x8 (&pb)[4], f32x16 (&O)[4]) {
;     {
;         const unsigned char* vb = sV + l31 * A_VROWB + 16 * h;
;         bf16x8 va[4], vc[4];
; #pragma unroll
;         for (int d = 0; d < 4; ++d) va[d] = *(const bf16x8*)(vb + d * 32 * A_VROWB);
;         __builtin_amdgcn_sched_barrier(0);
; #pragma unroll
;         for (int d = 0; d < 4; ++d) vc[d] = *(const bf16x8*)(vb + d * 32 * A_VROWB + 32);
;         __builtin_amdgcn_sched_barrier(0);
; #pragma unroll
;         for (int d = 0; d < 4; ++d) O[d] = MFMA32(va[d], pb[0], O[d]);
;         __builtin_amdgcn_sched_barrier(0);
; #pragma unroll
;         for (int d = 0; d < 4; ++d) va[d] = *(const bf16x8*)(vb + d * 32 * A_VROWB + 64);
;         __builtin_amdgcn_sched_barrier(0);
; #pragma unroll
;         for (int d = 0; d < 4; ++d) O[d] = MFMA32(vc[d], pb[1], O[d]);
;         __builtin_amdgcn_sched_barrier(0);
; #pragma unroll
;         for (int d = 0; d < 4; ++d) vc[d] = *(const bf16x8*)(vb + d * 32 * A_VROWB + 96);
;         __builtin_amdgcn_sched_barrier(0);
; #pragma unroll
;         for (int d = 0; d < 4; ++d) O[d] = MFMA32(va[d], pb[2], O[d]);
;         __builtin_amdgcn_sched_barrier(0);
; #pragma unroll
;         for (int d = 0; d < 4; ++d) O[d] = MFMA32(vc[d], pb[3], O[d]);
;     }
; DI void attn_item(const Params& p, unsigned char* lds, int b, int hd, int qb, float lam) {
;     ...
;     {
;         attn_s(lds + bc * A_STAGE, 0, qb, qs, sub, l31, h, qf, O, m, l, pb);
;         attn_pv(lds + bc * A_STAGE + A_KB, l31, h, pb, O);
;         A_STORE(k1r, v1r, bn);
;         __syncthreads();
;         bp = bc; bc = bn; bn = (bn == 2) ? 0 : bn + 1;
;     }
	ds_read_b128 v[26:29], v1 offset:8704
	ds_read_b128 v[30:33], v1 offset:8736
	ds_read_b128 v[34:37], v1 offset:8768
	ds_read_b128 v[38:41], v1 offset:8800
	v_mov_b32_e32 v10, v0
	v_mov_b32_e32 v11, v0
	v_mov_b32_e32 v12, v0
	v_mov_b32_e32 v13, v0
	v_mov_b32_e32 v14, v0
	v_mov_b32_e32 v15, v0
	v_mov_b32_e32 v1, v0
	v_mov_b32_e32 v2, v0
	v_mov_b32_e32 v3, v0
	v_mov_b32_e32 v4, v0
	v_mov_b32_e32 v5, v0
	v_mov_b32_e32 v6, v0
	v_mov_b32_e32 v7, v0
	v_mov_b32_e32 v8, v0
	v_mov_b32_e32 v9, v0
	v_mov_b64_e32 v[24:25], v[14:15]
	v_mov_b64_e32 v[22:23], v[12:13]
	v_mov_b64_e32 v[20:21], v[10:11]
	v_mov_b64_e32 v[18:19], v[8:9]
	v_mov_b64_e32 v[16:17], v[6:7]
	v_mov_b64_e32 v[14:15], v[4:5]
	v_mov_b64_e32 v[12:13], v[2:3]
	v_mov_b64_e32 v[10:11], v[0:1]
	s_waitcnt lgkmcnt(3)
	s_nop 0
	v_mfma_f32_32x32x16_bf16 v[10:25], v[26:29], v[100:103], v[10:25]
	s_waitcnt lgkmcnt(2)
	v_mfma_f32_32x32x16_bf16 v[10:25], v[30:33], v[104:107], v[10:25]
	s_waitcnt lgkmcnt(1)
	v_mfma_f32_32x32x16_bf16 v[10:25], v[34:37], v[108:111], v[10:25]
	v_max3_f32 v1, v188, v188, v188
	s_nop 0
	v_max3_f32 v2, v1, v1, v1
	s_waitcnt lgkmcnt(0)
	v_mfma_f32_32x32x16_bf16 v[10:25], v[38:41], v[112:115], v[10:25]
	v_max3_f32 v3, v188, v188, v18
	v_max3_f32 v4, v19, v20, v21
	v_max3_f32 v5, v22, v23, v24
	s_nop 0
	v_max3_f32 v1, v1, v3, v4
	s_nop 10
	v_max_f32_e32 v6, v25, v25
	v_max3_f32 v1, v2, v2, v1
	v_max_f32_e32 v6, 0xff800000, v6
	v_max3_f32 v1, v1, v5, v6
	s_nop 0
	v_mov_b32_e32 v2, v1
	s_nop 1
	v_permlane32_swap_b32_e32 v1, v2
	v_max_f32_e32 v2, v2, v2
	v_max_f32_e32 v1, v1, v1
	v_max_f32_e32 v86, v1, v2
	v_sub_f32_e32 v1, 0xff800000, v86
	v_sub_f32_e32 v19, v19, v86
	v_sub_f32_e32 v26, v18, v86
	v_sub_f32_e32 v21, v21, v86
	v_sub_f32_e32 v20, v20, v86
	v_exp_f32_e32 v18, v1
	v_exp_f32_e32 v26, v26
	v_exp_f32_e32 v27, v19
	v_sub_f32_e32 v23, v23, v86
	v_sub_f32_e32 v22, v22, v86
	v_exp_f32_e32 v28, v20
	v_exp_f32_e32 v29, v21
	v_sub_f32_e32 v25, v25, v86
	v_sub_f32_e32 v24, v24, v86
	v_exp_f32_e32 v30, v22
	v_exp_f32_e32 v31, v23
	v_exp_f32_e32 v32, v24
	v_exp_f32_e32 v33, v25
	v_pk_add_f32 v[34:35], v[18:19], v[26:27] op_sel_hi:[0,1]
	v_add_f32_e32 v36, v18, v18
	v_pk_add_f32 v[24:25], v[18:19], v[28:29] op_sel_hi:[0,1]
	v_mov_b32_e32 v37, v34
	v_mov_b32_e32 v34, v36
	v_pk_add_f32 v[22:23], v[18:19], v[30:31] op_sel_hi:[0,1]
	v_pk_add_f32 v[34:35], v[36:37], v[34:35]
	v_mov_b32_e32 v37, v24
	v_mov_b32_e32 v24, v36
	v_pk_add_f32 v[20:21], v[18:19], v[32:33] op_sel_hi:[0,1]
	v_pk_add_f32 v[24:25], v[36:37], v[24:25]
	v_mov_b32_e32 v37, v22
	v_mov_b32_e32 v22, v36
	v_pk_add_f32 v[22:23], v[36:37], v[22:23]
	v_mov_b32_e32 v37, v20
	v_mov_b32_e32 v20, v36
	v_pk_add_f32 v[20:21], v[36:37], v[20:21]
	v_cvt_pk_bf16_f32 v88, v18, v18
	v_lshlrev_b32_e32 v18, 7, v146
	v_pk_add_f32 v[24:25], v[34:35], v[24:25]
	v_pk_add_f32 v[20:21], v[22:23], v[20:21]
	v_sub_u32_e32 v18, v42, v18
	v_pk_add_f32 v[20:21], v[24:25], v[20:21]
	v_add_u32_e32 v185, v18, v98
	v_add_f32_e32 v1, v20, v21
	ds_read_b128 v[160:163], v185 offset:17504
	ds_read_b128 v[164:167], v185 offset:22112
	ds_read_b128 v[168:171], v185 offset:26720
	ds_read_b128 v[172:175], v185 offset:31328
	v_exp_f32_e64 v184, -v86
	v_mov_b32_e32 v89, v88
	v_mov_b32_e32 v90, v88
	v_mov_b32_e32 v91, v88
	v_mul_f32_e32 v2, 0, v184
	v_mov_b32_e32 v3, v2
	v_mov_b32_e32 v4, v2
	v_mov_b32_e32 v5, v2
	v_mov_b32_e32 v6, v2
	v_mov_b32_e32 v7, v2
	v_mov_b32_e32 v8, v2
	v_mov_b32_e32 v9, v2
	v_mov_b32_e32 v10, v2
	v_mov_b32_e32 v11, v2
	v_mov_b32_e32 v12, v2
	v_mov_b32_e32 v13, v2
	v_mov_b32_e32 v14, v2
	v_mov_b32_e32 v15, v2
	v_mov_b32_e32 v16, v2
	v_mov_b32_e32 v17, v2
	v_cvt_pk_bf16_f32 v156, v26, v27
	v_cvt_pk_bf16_f32 v157, v28, v29
	v_cvt_pk_bf16_f32 v158, v30, v31
	v_cvt_pk_bf16_f32 v159, v32, v33
	s_waitcnt lgkmcnt(3)
	v_mfma_f32_32x32x16_bf16 v[50:65], v[160:163], v[156:159], v[2:17]
	s_waitcnt vmcnt(3)
	ds_write_b128 v87, v[74:77] offset:35840
	s_waitcnt vmcnt(1)
	ds_write_b128 v96, v[78:81] offset:35840
	v_add_u32_e32 v74, 0xd000, v97
	ds_write2_b64 v74, v[70:71], v[72:73] offset1:2
	v_add_u32_e32 v70, 0xd000, v155
	v_fmac_f32_e32 v1, 0, v184
	s_cmpk_gt_u32 s4, 0x7f
	s_waitcnt vmcnt(0)
	ds_write2_b64 v70, v[66:67], v[68:69] offset1:2
	s_waitcnt lgkmcnt(6)
	v_mfma_f32_32x32x16_bf16 v[34:49], v[164:167], v[156:159], v[2:17]
	s_waitcnt lgkmcnt(0)
	s_barrier
	v_mfma_f32_32x32x16_bf16 v[18:33], v[168:171], v[156:159], v[2:17]
	v_mfma_f32_32x32x16_bf16 v[2:17], v[172:175], v[156:159], v[2:17]
	s_cbranch_scc1 .LBB0_1824
	s_lshr_b32 s4, s4, 1
	s_lshl_b32 s5, s5, 1
	s_and_b32 s4, s4, 0x7ffffff8
	s_lshl_b32 s0, s0, 1
	s_or_b32 s4, s5, s4
	v_mul_u32_u24_e32 v155, 0x110, v146
	v_mul_u32_u24_e32 v156, 0x90, v146
	s_mov_b32 s13, 1
	s_add_i32 s6, s0, 3
	v_lshl_add_u64 v[142:143], v[84:85], 0, s[88:89]
	v_lshl_add_u64 v[142:143], v[142:143], 0, s[88:89]
	v_add_f32_e32 v157, 0, v86
	v_lshl_add_u64 v[144:145], v[82:83], 0, s[90:91]
	v_lshl_add_u64 v[144:145], v[144:145], 0, s[90:91]
	s_mov_b32 s7, 2
	v_lshl_or_b32 v158, v149, 2, 59
	s_sub_i32 s11, 0, s4
	s_movk_i32 s12, 0xffc0
	v_xor_b32_e32 v240, 0x80000000, v157
	v_mov_b32_e32 v241, v240
	v_mov_b32_e32 v242, v240
	v_mov_b32_e32 v243, v240
	v_mov_b32_e32 v244, v240
	v_mov_b32_e32 v245, v240
	v_mov_b32_e32 v246, v240
	v_mov_b32_e32 v247, v240
	v_mov_b32_e32 v248, v240
	v_mov_b32_e32 v249, v240
	v_mov_b32_e32 v250, v240
	v_mov_b32_e32 v251, v240
	v_mov_b32_e32 v252, v240
	v_mov_b32_e32 v253, v240
	v_mov_b32_e32 v254, v240
	v_mov_b32_e32 v255, v240
	v_readfirstlane_b32 s99, v147
	s_cmp_eq_u32 s99, 1
	s_cbranch_scc0 .Lpipe_nooffs
	s_barrier
